# added GLA-local state-update block with batched LDS reads on top of the previous stack
# speedup vs baseline: 1.0032x; 1.0032x over previous
.LBB0_1200:
	s_or_b64 exec, exec, s[14:15]
	v_mov_b32_e32 v78, v115
	v_mov_b32_e32 v2, v113
	s_waitcnt lgkmcnt(0)
	s_barrier
	s_add_i32 s37, s37, 1
	v_lshl_add_u32 v2, v2, 4, 0
	v_add_u32_e32 v76, 0x15800, v2
	ds_read_b128 v[160:163], v76
	ds_read_b128 v[164:167], v76 offset:64
	ds_read_b128 v[168:171], v76 offset:128
	ds_read_b128 v[172:175], v76 offset:192
	ds_read_b128 v[176:179], v76 offset:256
	ds_read_b128 v[180:183], v76 offset:320
	ds_read_b128 v[184:187], v76 offset:384
	ds_read_b128 v[188:191], v76 offset:448
	v_add_u32_e32 v72, s13, v78
	s_add_i32 s39, s39, -1
	v_mad_u64_u32 v[76:77], s[10:11], v72, s87, v[2:3]
	v_mad_u64_u32 v[78:79], s[10:11], v78, s87, v[2:3]
	s_cmp_eq_u32 s37, 4
	ds_read_b128 v[192:195], v76 offset:35840
	ds_read_b128 v[196:199], v76 offset:38144
	ds_read_b128 v[200:203], v78 offset:17408
	ds_read_b128 v[206:209], v78 offset:19712
	ds_read_b128 v[210:213], v78 offset:22016
	ds_read_b128 v[214:217], v78 offset:24320
	s_waitcnt lgkmcnt(6)
	v_pk_mul_f32 v[64:65], v[64:65], v[160:161]
	v_pk_mul_f32 v[66:67], v[66:67], v[162:163]
	v_pk_mul_f32 v[60:61], v[60:61], v[160:161]
	v_pk_mul_f32 v[62:63], v[62:63], v[162:163]
	v_pk_mul_f32 v[56:57], v[56:57], v[164:165]
	v_pk_mul_f32 v[58:59], v[58:59], v[166:167]
	v_pk_mul_f32 v[52:53], v[52:53], v[164:165]
	v_pk_mul_f32 v[54:55], v[54:55], v[166:167]
	v_pk_mul_f32 v[48:49], v[48:49], v[168:169]
	v_pk_mul_f32 v[50:51], v[50:51], v[170:171]
	v_pk_mul_f32 v[44:45], v[44:45], v[168:169]
	v_pk_mul_f32 v[46:47], v[46:47], v[170:171]
	v_pk_mul_f32 v[40:41], v[40:41], v[172:173]
	v_pk_mul_f32 v[42:43], v[42:43], v[174:175]
	v_pk_mul_f32 v[36:37], v[36:37], v[172:173]
	v_pk_mul_f32 v[38:39], v[38:39], v[174:175]
	v_pk_mul_f32 v[32:33], v[32:33], v[176:177]
	v_pk_mul_f32 v[34:35], v[34:35], v[178:179]
	v_pk_mul_f32 v[28:29], v[28:29], v[176:177]
	v_pk_mul_f32 v[30:31], v[30:31], v[178:179]
	v_pk_mul_f32 v[24:25], v[24:25], v[180:181]
	v_pk_mul_f32 v[26:27], v[26:27], v[182:183]
	v_pk_mul_f32 v[20:21], v[20:21], v[180:181]
	v_pk_mul_f32 v[22:23], v[22:23], v[182:183]
	v_pk_mul_f32 v[12:13], v[12:13], v[184:185]
	v_pk_mul_f32 v[14:15], v[14:15], v[186:187]
	v_pk_mul_f32 v[4:5], v[4:5], v[184:185]
	v_pk_mul_f32 v[6:7], v[6:7], v[186:187]
	v_pk_mul_f32 v[16:17], v[16:17], v[188:189]
	v_pk_mul_f32 v[18:19], v[18:19], v[190:191]
	v_pk_mul_f32 v[8:9], v[8:9], v[188:189]
	v_pk_mul_f32 v[10:11], v[10:11], v[190:191]
	ds_read_b128 v[218:221], v78 offset:26624
	ds_read_b128 v[224:227], v78 offset:28928
	ds_read_b128 v[232:235], v78 offset:31232
	ds_read_b128 v[236:239], v78 offset:33536
	s_waitcnt lgkmcnt(4)
	v_mfma_f32_16x16x32_f16 v[64:67], v[200:203], v[192:195], v[64:67]
	v_mfma_f32_16x16x32_f16 v[60:63], v[200:203], v[196:199], v[60:63]
	v_mfma_f32_16x16x32_f16 v[56:59], v[206:209], v[192:195], v[56:59]
	v_mfma_f32_16x16x32_f16 v[52:55], v[206:209], v[196:199], v[52:55]
	v_mfma_f32_16x16x32_f16 v[48:51], v[210:213], v[192:195], v[48:51]
	v_mfma_f32_16x16x32_f16 v[44:47], v[210:213], v[196:199], v[44:47]
	v_mfma_f32_16x16x32_f16 v[40:43], v[214:217], v[192:195], v[40:43]
	v_mfma_f32_16x16x32_f16 v[36:39], v[214:217], v[196:199], v[36:39]
	ds_read_b128 v[240:243], v76 offset:35904
	ds_read_b128 v[244:247], v76 offset:38208
	ds_read_b128 v[160:163], v78 offset:17472
	ds_read_b128 v[164:167], v78 offset:19776
	ds_read_b128 v[168:171], v78 offset:22080
	ds_read_b128 v[172:175], v78 offset:24384
	s_waitcnt lgkmcnt(6)
	v_mfma_f32_16x16x32_f16 v[32:35], v[218:221], v[192:195], v[32:35]
	v_mfma_f32_16x16x32_f16 v[28:31], v[218:221], v[196:199], v[28:31]
	v_mfma_f32_16x16x32_f16 v[24:27], v[224:227], v[192:195], v[24:27]
	v_mfma_f32_16x16x32_f16 v[20:23], v[224:227], v[196:199], v[20:23]
	v_mfma_f32_16x16x32_f16 v[12:15], v[232:235], v[192:195], v[12:15]
	v_mfma_f32_16x16x32_f16 v[4:7], v[232:235], v[196:199], v[4:7]
	v_mfma_f32_16x16x32_f16 v[16:19], v[236:239], v[192:195], v[16:19]
	v_mfma_f32_16x16x32_f16 v[8:11], v[236:239], v[196:199], v[8:11]
	ds_read_b128 v[176:179], v78 offset:26688
	ds_read_b128 v[180:183], v78 offset:28992
	ds_read_b128 v[184:187], v78 offset:31296
	ds_read_b128 v[188:191], v78 offset:33600
	s_waitcnt lgkmcnt(4)
	v_mfma_f32_16x16x32_f16 v[64:67], v[160:163], v[240:243], v[64:67]
	v_mfma_f32_16x16x32_f16 v[60:63], v[160:163], v[244:247], v[60:63]
	v_mfma_f32_16x16x32_f16 v[56:59], v[164:167], v[240:243], v[56:59]
	v_mfma_f32_16x16x32_f16 v[52:55], v[164:167], v[244:247], v[52:55]
	v_mfma_f32_16x16x32_f16 v[48:51], v[168:171], v[240:243], v[48:51]
	v_mfma_f32_16x16x32_f16 v[44:47], v[168:171], v[244:247], v[44:47]
	v_mfma_f32_16x16x32_f16 v[40:43], v[172:175], v[240:243], v[40:43]
	v_mfma_f32_16x16x32_f16 v[36:39], v[172:175], v[244:247], v[36:39]
	s_waitcnt lgkmcnt(0)
	v_mfma_f32_16x16x32_f16 v[32:35], v[176:179], v[240:243], v[32:35]
	v_mfma_f32_16x16x32_f16 v[28:31], v[176:179], v[244:247], v[28:31]
	v_mfma_f32_16x16x32_f16 v[24:27], v[180:183], v[240:243], v[24:27]
	v_mfma_f32_16x16x32_f16 v[20:23], v[180:183], v[244:247], v[20:23]
	v_mfma_f32_16x16x32_f16 v[12:15], v[184:187], v[240:243], v[12:15]
	v_mfma_f32_16x16x32_f16 v[4:7], v[184:187], v[244:247], v[4:7]
	v_mfma_f32_16x16x32_f16 v[16:19], v[188:191], v[240:243], v[16:19]
	v_mfma_f32_16x16x32_f16 v[8:11], v[188:191], v[244:247], v[8:11]
	s_cbranch_scc1 .LBB0_1214
